# P2 conversion items: HGRN workgroups back to their original share; [1536,2048) done as second item by the three-gate-tile workgroups idx >= 64 (they have slack), [1024,1536) by the two-gate-tile workg
# speedup vs baseline: 1.0035x; 1.0035x over previous
;     ...
;     { int it = (PART == 0 ? gw : I_IN + gw); const int end = (PART == 0 ? I_IN : (I_IN + it_last < NITEMS ? I_IN + it_last : NITEMS));
;       if (it < end) {
;         ConvItem pa = conv_item(a, ws, it), pb = pa; float wa[32], wb[32]; f32x4 ka[2], kb[2];
;         conv_load(pa, wa, ka, lane);
;         for (;;) {
;             const bool hb = it + NGW < end; if (hb) { pb = conv_item(a, ws, it + NGW); conv_load(pb, wb, kb, lane); }
;             conv_finish(pa, wa, ka, scr, lane);
;             if (!hb) break; it += NGW;
;             const bool ha = it + NGW < end; if (ha) { pa = conv_item(a, ws, it + NGW); conv_load(pa, wa, ka, lane); }
;             conv_finish(pb, wb, kb, scr, lane);
;             if (!ha) break; it += NGW;
;         }
;       }
;     }
.LBB0_534:
	s_cmpk_gt_i32 s18, 0x1ff
	s_cselect_b64 s[12:13], -1, 0
	s_cmpk_lt_i32 s18, 0x200
	s_mov_b64 s[4:5], s[2:3]
	s_mov_b32 s10, s21
	s_mov_b32 s11, s0
	s_mov_b32 s8, s6
	s_mov_b32 s22, s20
	s_cbranch_scc1 .LBB0_544
	s_add_i32 s1, s18, 0x1600
	s_and_b64 vcc, exec, s[14:15]
	s_cbranch_vccz .LBB0_537
	s_add_u32 s4, s72, 0x1a00000
	s_addc_u32 s5, s73, 0
	s_add_i32 s7, s1, 0xe800
	s_and_b32 s8, s7, 0xffff
	s_mul_i32 s8, s8, 0xba2f
	s_lshr_b32 s8, s8, 23
	s_mul_i32 s9, s8, 0xb0
	s_sub_i32 s7, s7, s9
	s_and_b32 s9, s7, 0xffff
	s_lshl_b32 s22, s9, 5
	s_bfe_i32 s7, s7, 0x10002
	s_lshl_b32 s9, s9, 4
	s_and_b32 s7, s7, 0xb00
	s_and_b32 s9, s9, 0xf80
	v_readlane_b32 s24, v254, 0
	s_add_i32 s7, s7, s9
	s_and_b32 s9, s22, 0x60
	v_readlane_b32 s28, v254, 4
	v_readlane_b32 s29, v254, 5
	v_readlane_b32 s30, v254, 6
	v_readlane_b32 s31, v254, 7
	s_lshl_b32 s8, s8, 6
	s_or_b32 s10, s7, s9
	s_mov_b64 s[18:19], 0
	v_readlane_b32 s25, v254, 1
	v_readlane_b32 s26, v254, 2
	v_readlane_b32 s27, v254, 3
	s_mov_b64 s[14:15], s[28:29]
	s_mov_b64 s[16:17], s[30:31]
	s_branch .LBB0_538
